# attention epilogue head: first seven up-projection weight loads issued before the overflow vote instead of after it
# speedup vs baseline: 1.0036x; 1.0026x over previous
.LBB0_893:
	v_mov_b32_e32 v1, v244
	v_lshlrev_b32_e32 v98, 5, v206
	v_bfe_u32 v157, v1, 5, 1
	v_and_b32_e32 v156, 31, v1
	v_lshlrev_b32_e32 v66, 9, v157
	v_mov_b32_e32 v67, v0
	v_lshl_add_u64 v[66:67], s[38:39], 0, v[66:67]
	v_lshlrev_b32_e32 v68, 4, v156
	v_mov_b32_e32 v69, v0
	v_ashrrev_i32_e32 v99, 31, v98
	v_lshl_add_u64 v[100:101], v[66:67], 0, v[68:69]
	v_lshlrev_b64 v[66:67], 10, v[98:99]
	v_lshl_add_u64 v[74:75], v[100:101], 0, v[66:67]
	global_load_dwordx4 v[66:69], v[74:75], off
	v_or_b32_e32 v70, 8, v98
	v_ashrrev_i32_e32 v71, 31, v70
	v_lshlrev_b64 v[70:71], 10, v[70:71]
	v_lshl_add_u64 v[76:77], v[100:101], 0, v[70:71]
	global_load_dwordx4 v[70:73], v[76:77], off
	global_load_dwordx4 v[102:105], v[74:75], off offset:1024
	global_load_dwordx4 v[106:109], v[76:77], off offset:1024
	global_load_dwordx4 v[110:113], v[74:75], off offset:2048
	global_load_dwordx4 v[114:117], v[76:77], off offset:2048
	global_load_dwordx4 v[118:121], v[74:75], off offset:3072
	s_cmp_lg_u32 s78, 0
	s_cbranch_scc1 .Lopt_done
	v_cmp_ngt_f32_e32 vcc, 0x71800000, v173
	s_cmp_eq_u64 vcc, 0
	s_cbranch_scc1 .Lopt_vote
	v_mov_b32_e32 v209, 0x23ff8
	v_mov_b32_e32 v245, 1
	ds_write_b32 v209, v245
.Lopt_vote:
	s_waitcnt lgkmcnt(0)
	s_barrier
	v_mov_b32_e32 v209, 0x23ff8
	ds_read_b32 v245, v209
	s_waitcnt lgkmcnt(0)
	v_readfirstlane_b32 s79, v245
	s_cmp_eq_u32 s79, 0
	s_cbranch_scc1 .Lopt_done
	s_barrier
	v_mov_b32_e32 v245, 0
	ds_write_b32 v209, v245
	s_waitcnt lgkmcnt(0)
	s_mov_b32 s78, 1
	s_branch .LBB0_879
.Lopt_done:
	s_mov_b32 s78, 0
	v_and_b32_e32 v79, 64, v191
	v_xor_b32_e32 v78, 32, v191
	v_add_u32_e32 v79, 64, v79
	v_cmp_lt_i32_e32 vcc, v78, v79
	global_load_dwordx4 v[122:125], v[76:77], off offset:3072
	v_ashrrev_i32_e32 v158, 6, v1
	v_cndmask_b32_e32 v78, v191, v78, vcc
	v_lshlrev_b32_e32 v78, 2, v78
	ds_bpermute_b32 v78, v78, v173
	v_add_co_u32_e32 v134, vcc, s37, v74
	v_bfe_u32 v160, v1, 4, 2
	s_nop 0
	v_addc_co_u32_e32 v135, vcc, 0, v75, vcc
	s_waitcnt lgkmcnt(0)
	v_add_f32_e32 v74, v173, v78
	v_div_scale_f32 v75, s[8:9], v74, v74, 1.0
	v_add_co_u32_e32 v136, vcc, s37, v76
	global_load_dwordx4 v[126:129], v[134:135], off
	v_rcp_f32_e32 v76, v75
	v_addc_co_u32_e32 v137, vcc, 0, v77, vcc
	v_div_scale_f32 v77, vcc, 1.0, v74, 1.0
	v_fma_f32 v78, -v75, v76, 1.0
	v_fmac_f32_e32 v76, v78, v76
	v_mul_f32_e32 v78, v77, v76
	v_fma_f32 v79, -v75, v78, v77
	v_fmac_f32_e32 v78, v79, v76
	v_fma_f32 v75, -v75, v78, v77
	v_div_fmas_f32 v75, v75, v76, v78
	v_div_fixup_f32 v138, v75, v74, 1.0
	v_mul_f32_e32 v50, v138, v50
	v_mul_f32_e32 v51, v138, v51
	v_mul_f32_e32 v52, v138, v52
	v_mul_f32_e32 v53, v138, v53
	v_mul_f32_e32 v54, v138, v54
	v_mul_f32_e32 v55, v138, v55
	v_mul_f32_e32 v56, v138, v56
	v_mul_f32_e32 v57, v138, v57
	v_cvt_pk_bf16_f32 v50, v50, v51
	v_cvt_pk_bf16_f32 v51, v52, v53
	v_cvt_pk_bf16_f32 v52, v54, v55
	v_cvt_pk_bf16_f32 v53, v56, v57
	global_load_dwordx4 v[54:57], v[136:137], off
	global_load_dwordx4 v[130:133], v[134:135], off offset:1024
	v_mul_f32_e32 v58, v138, v58
	v_mul_f32_e32 v59, v138, v59
	v_mul_f32_e32 v60, v138, v60
	v_mul_f32_e32 v61, v138, v61
	v_mul_f32_e32 v62, v138, v62
	v_mul_f32_e32 v63, v138, v63
	v_mul_f32_e32 v64, v138, v64
	v_mul_f32_e32 v65, v138, v65
	v_cvt_pk_bf16_f32 v58, v58, v59
	v_cvt_pk_bf16_f32 v59, v60, v61
	v_cvt_pk_bf16_f32 v60, v62, v63
	v_cvt_pk_bf16_f32 v61, v64, v65
	v_mul_f32_e32 v34, v138, v34
	v_mul_f32_e32 v35, v138, v35
	v_mul_f32_e32 v36, v138, v36
	v_mul_f32_e32 v37, v138, v37
	v_mul_f32_e32 v38, v138, v38
	v_mul_f32_e32 v39, v138, v39
	v_mul_f32_e32 v40, v138, v40
	v_mul_f32_e32 v41, v138, v41
	v_mul_f32_e32 v42, v138, v42
	v_mul_f32_e32 v43, v138, v43
	v_mul_f32_e32 v44, v138, v44
	v_mul_f32_e32 v45, v138, v45
	v_mul_f32_e32 v46, v138, v46
	v_mul_f32_e32 v47, v138, v47
	v_mul_f32_e32 v48, v138, v48
	v_mul_f32_e32 v49, v138, v49
	v_mul_f32_e32 v18, v138, v18
	v_mul_f32_e32 v19, v138, v19
	v_mul_f32_e32 v20, v138, v20
	v_mul_f32_e32 v21, v138, v21
	v_mul_f32_e32 v22, v138, v22
	v_mul_f32_e32 v23, v138, v23
	v_mul_f32_e32 v24, v138, v24
	v_mul_f32_e32 v25, v138, v25
	v_mul_f32_e32 v26, v138, v26
	v_mul_f32_e32 v27, v138, v27
	v_mul_f32_e32 v28, v138, v28
	v_mul_f32_e32 v29, v138, v29
	v_mul_f32_e32 v30, v138, v30
	v_mul_f32_e32 v31, v138, v31
	v_mul_f32_e32 v32, v138, v32
	v_mul_f32_e32 v33, v138, v33
	v_mul_f32_e32 v2, v138, v2
	v_mul_f32_e32 v3, v138, v3
	v_mul_f32_e32 v4, v138, v4
	v_mul_f32_e32 v5, v138, v5
	s_waitcnt vmcnt(10)
	v_mfma_f32_32x32x16_bf16 v[82:97], v[66:69], v[50:53], 0
	v_mul_f32_e64 v6, v6, v138
	v_mul_f32_e64 v7, v7, v138
	v_mul_f32_e64 v8, v8, v138
	v_mul_f32_e64 v9, v9, v138
	v_mul_f32_e64 v10, v10, v138
	v_mul_f32_e64 v11, v11, v138
	v_ashrrev_i32_e32 v173, 31, v172
	v_lshlrev_b32_e32 v1, 4, v1
	v_and_b32_e32 v154, 0xf0, v1
	v_mov_b32_e32 v155, v0
	s_waitcnt vmcnt(9)
	v_mfma_f32_32x32x16_bf16 v[66:81], v[70:73], v[50:53], 0
	v_mul_lo_u32 v1, v158, s45
	v_add_u32_e32 v1, 0, v1
	s_mov_b32 s14, 0
	s_waitcnt vmcnt(8)
	v_mfma_f32_32x32x16_bf16 v[82:97], v[102:105], v[58:61], v[82:97]
	global_load_dwordx4 v[62:65], v[134:135], off offset:2048
	global_load_dwordx4 v[102:105], v[134:135], off offset:3072
	s_waitcnt vmcnt(9)
	v_mfma_f32_32x32x16_bf16 v[66:81], v[106:109], v[58:61], v[66:81]
	v_cvt_pk_bf16_f32 v106, v34, v35
	v_cvt_pk_bf16_f32 v107, v36, v37
	v_cvt_pk_bf16_f32 v108, v38, v39
	v_cvt_pk_bf16_f32 v109, v40, v41
	global_load_dwordx4 v[34:37], v[136:137], off offset:1024
	global_load_dwordx4 v[38:41], v[136:137], off offset:2048
	s_waitcnt vmcnt(10)
	v_mfma_f32_32x32x16_bf16 v[82:97], v[110:113], v[106:109], v[82:97]
	v_cvt_pk_bf16_f32 v110, v42, v43
	v_cvt_pk_bf16_f32 v111, v44, v45
	global_load_dwordx4 v[42:45], v[136:137], off offset:3072
	v_cvt_pk_bf16_f32 v112, v46, v47
	v_or_b32_e32 v46, 16, v98
	v_ashrrev_i32_e32 v47, 31, v46
	v_lshlrev_b64 v[46:47], 10, v[46:47]
	v_lshl_add_u64 v[134:135], v[100:101], 0, v[46:47]
	s_waitcnt vmcnt(10)
	v_mfma_f32_32x32x16_bf16 v[66:81], v[114:117], v[106:109], v[66:81]
	v_cvt_pk_bf16_f32 v113, v48, v49
	v_cvt_pk_bf16_f32 v114, v18, v19
	v_cvt_pk_bf16_f32 v115, v20, v21
	v_cvt_pk_bf16_f32 v116, v22, v23
	v_cvt_pk_bf16_f32 v117, v24, v25
	global_load_dwordx4 v[18:21], v[134:135], off
	global_load_dwordx4 v[22:25], v[134:135], off offset:1024
	global_load_dwordx4 v[46:49], v[134:135], off offset:2048
	s_waitcnt vmcnt(12)
	v_mfma_f32_32x32x16_bf16 v[82:97], v[118:121], v[110:113], v[82:97]
	v_cvt_pk_bf16_f32 v118, v26, v27
	v_cvt_pk_bf16_f32 v119, v28, v29
	v_cvt_pk_bf16_f32 v120, v30, v31
	v_cvt_pk_bf16_f32 v121, v32, v33
	global_load_dwordx4 v[26:29], v[134:135], off offset:3072
	s_waitcnt vmcnt(12)
	v_mfma_f32_32x32x16_bf16 v[66:81], v[122:125], v[110:113], v[66:81]
	v_cvt_pk_bf16_f32 v122, v2, v3
	v_cvt_pk_bf16_f32 v123, v4, v5
	v_cvt_pk_bf16_f32 v124, v6, v7
	v_cvt_pk_bf16_f32 v125, v8, v9
	v_mul_f32_e64 v2, v12, v138
	v_mul_f32_e64 v3, v13, v138
	v_mul_f32_e32 v4, v138, v14
	v_mul_f32_e32 v5, v138, v15
	v_mul_f32_e32 v6, v138, v16
	v_mul_f32_e32 v7, v138, v17
	s_waitcnt vmcnt(11)
	v_mfma_f32_32x32x16_bf16 v[82:97], v[126:129], v[114:117], v[82:97]
	s_waitcnt vmcnt(10)
	v_mfma_f32_32x32x16_bf16 v[66:81], v[54:57], v[114:117], v[66:81]
	s_waitcnt vmcnt(9)
	v_mfma_f32_32x32x16_bf16 v[82:97], v[130:133], v[118:121], v[82:97]
	s_waitcnt vmcnt(6)
	v_mfma_f32_32x32x16_bf16 v[66:81], v[34:37], v[118:121], v[66:81]
	v_mfma_f32_32x32x16_bf16 v[82:97], v[62:65], v[122:125], v[82:97]
	v_cvt_pk_bf16_f32 v63, v2, v3
	v_add_co_u32_e32 v2, vcc, s37, v134
	v_cvt_pk_bf16_f32 v62, v10, v11
	s_nop 0
	v_addc_co_u32_e32 v3, vcc, 0, v135, vcc
	global_load_dwordx4 v[30:33], v[2:3], off
	global_load_dwordx4 v[34:37], v[2:3], off offset:1024
	s_waitcnt vmcnt(7)
	v_mfma_f32_32x32x16_bf16 v[66:81], v[38:41], v[122:125], v[66:81]
	v_cvt_pk_bf16_f32 v64, v4, v5
	v_cvt_pk_bf16_f32 v65, v6, v7
	s_waitcnt vmcnt(6)
	s_nop 0
	v_mfma_f32_32x32x16_bf16 v[66:81], v[42:45], v[62:65], v[66:81]
	global_load_dwordx4 v[38:41], v[2:3], off offset:2048
	global_load_dwordx4 v[42:45], v[2:3], off offset:3072
	s_waitcnt vmcnt(7)
	v_mfma_f32_32x32x16_bf16 v[2:17], v[18:21], v[50:53], 0
	v_or_b32_e32 v18, 24, v98
	v_ashrrev_i32_e32 v19, 31, v18
	v_lshlrev_b64 v[18:19], 10, v[18:19]
	v_lshl_add_u64 v[54:55], v[100:101], 0, v[18:19]
	global_load_dwordx4 v[18:21], v[54:55], off
	global_load_dwordx4 v[98:101], v[54:55], off offset:1024
	v_mfma_f32_32x32x16_bf16 v[82:97], v[102:105], v[62:65], v[82:97]
	global_load_dwordx4 v[102:105], v[54:55], off offset:2048
	global_load_dwordx4 v[126:129], v[54:55], off offset:3072
	s_waitcnt vmcnt(10)
	v_mfma_f32_32x32x16_bf16 v[2:17], v[22:25], v[58:61], v[2:17]
	v_add_co_u32_e32 v22, vcc, s37, v54
	v_mov_b32_e32 v24, s55
	s_nop 0
	v_addc_co_u32_e32 v23, vcc, 0, v55, vcc
	global_load_dwordx4 v[130:133], v[22:23], off
	global_load_dwordx4 v[134:137], v[22:23], off offset:1024
	global_load_dwordx4 v[138:141], v[22:23], off offset:2048
	global_load_dwordx4 v[142:145], v[22:23], off offset:3072
	s_waitcnt vmcnt(13)
	v_mfma_f32_32x32x16_bf16 v[2:17], v[46:49], v[106:109], v[2:17]
	v_lshlrev_b32_e32 v22, 5, v158
	v_and_b32_e32 v159, 0x60, v22
	v_lshlrev_b64 v[22:23], 12, v[172:173]
	v_bitop3_b32 v24, v159, s44, v24 bitop3:0xc8
	v_or3_b32 v22, v22, v24, v160
	v_lshlrev_b64 v[22:23], 8, v[22:23]
	s_waitcnt vmcnt(12)
	v_mfma_f32_32x32x16_bf16 v[2:17], v[26:29], v[110:113], v[2:17]
	s_waitcnt vmcnt(11)
	v_mfma_f32_32x32x16_bf16 v[2:17], v[30:33], v[114:117], v[2:17]
	s_waitcnt vmcnt(10)
	v_mfma_f32_32x32x16_bf16 v[2:17], v[34:37], v[118:121], v[2:17]
	v_lshl_add_u64 v[34:35], s[22:23], 0, v[22:23]
	v_lshl_add_u64 v[34:35], v[34:35], 0, v[154:155]
	s_waitcnt vmcnt(7)
	v_mfma_f32_32x32x16_bf16 v[18:33], v[18:21], v[50:53], 0
	global_load_dwordx4 v[146:149], v[34:35], off
	global_load_dwordx4 v[150:153], v[34:35], off offset:1024
	global_load_dwordx4 v[54:57], v[34:35], off offset:2048
	global_load_dwordx4 v[50:53], v[34:35], off offset:3072
	v_add_co_u32_e32 v34, vcc, s37, v34
	s_nop 1
	v_addc_co_u32_e32 v35, vcc, 0, v35, vcc
	s_waitcnt vmcnt(10)
	v_mfma_f32_32x32x16_bf16 v[18:33], v[98:101], v[58:61], v[18:33]
	v_mul_u32_u24_e32 v98, 0x110, v156
	v_lshlrev_b32_e32 v99, 5, v157
	v_cvt_pk_f16_f32 v58, v82, v83
	v_add3_u32 v82, v1, v98, v99
	v_cvt_pk_f16_f32 v59, v84, v85
	v_cvt_pk_f16_f32 v60, v86, v87
	v_cvt_pk_f16_f32 v61, v88, v89
	s_waitcnt vmcnt(9)
	v_mfma_f32_32x32x16_bf16 v[18:33], v[102:105], v[106:109], v[18:33]
	s_waitcnt vmcnt(8)
	v_mfma_f32_32x32x16_bf16 v[18:33], v[126:129], v[110:113], v[18:33]
	s_waitcnt vmcnt(7)
	v_mfma_f32_32x32x16_bf16 v[18:33], v[130:133], v[114:117], v[18:33]
	s_waitcnt vmcnt(6)
	v_mfma_f32_32x32x16_bf16 v[18:33], v[134:137], v[118:121], v[18:33]
	v_mfma_f32_32x32x16_bf16 v[2:17], v[38:41], v[122:125], v[2:17]
	s_waitcnt vmcnt(5)
	v_mfma_f32_32x32x16_bf16 v[18:33], v[138:141], v[122:125], v[18:33]
	v_mfma_f32_32x32x16_bf16 v[2:17], v[42:45], v[62:65], v[2:17]
	global_load_dwordx4 v[46:49], v[34:35], off
	global_load_dwordx4 v[42:45], v[34:35], off offset:1024
	global_load_dwordx4 v[38:41], v[34:35], off offset:2048
	s_nop 0
	global_load_dwordx4 v[34:37], v[34:35], off offset:3072
	ds_write_b128 v82, v[58:61] offset:49152
	v_cvt_pk_f16_f32 v58, v90, v91
	v_cvt_pk_f16_f32 v59, v92, v93
	v_cvt_pk_f16_f32 v60, v94, v95
	v_cvt_pk_f16_f32 v61, v96, v97
	ds_write_b128 v82, v[58:61] offset:49168
	s_waitcnt vmcnt(8)
	v_mfma_f32_32x32x16_bf16 v[18:33], v[142:145], v[62:65], v[18:33]
	v_cvt_pk_f16_f32 v2, v2, v3
	v_cvt_pk_f16_f32 v3, v4, v5
	v_cvt_pk_f16_f32 v4, v6, v7
	v_cvt_pk_f16_f32 v5, v8, v9
	ds_write_b128 v82, v[2:5] offset:49280
	v_cvt_pk_f16_f32 v2, v10, v11
	v_cvt_pk_f16_f32 v3, v12, v13
	v_cvt_pk_f16_f32 v4, v14, v15
	v_cvt_pk_f16_f32 v5, v16, v17
	ds_write_b128 v82, v[2:5] offset:49296
	s_nop 1
	v_cvt_pk_f16_f32 v2, v18, v19
	v_cvt_pk_f16_f32 v3, v20, v21
	v_cvt_pk_f16_f32 v4, v22, v23
	v_cvt_pk_f16_f32 v5, v24, v25
	v_cvt_pk_f16_f32 v58, v66, v67
	v_cvt_pk_f16_f32 v59, v68, v69
	v_cvt_pk_f16_f32 v60, v70, v71
	v_cvt_pk_f16_f32 v61, v72, v73
	ds_write_b128 v82, v[2:5] offset:49344
	v_cvt_pk_f16_f32 v2, v26, v27
	v_cvt_pk_f16_f32 v3, v28, v29
	v_cvt_pk_f16_f32 v4, v30, v31
	v_cvt_pk_f16_f32 v5, v32, v33
	ds_write_b128 v82, v[58:61] offset:49216
	v_cvt_pk_f16_f32 v58, v74, v75
	v_cvt_pk_f16_f32 v59, v76, v77
	v_cvt_pk_f16_f32 v60, v78, v79
	v_cvt_pk_f16_f32 v61, v80, v81
	ds_write_b128 v82, v[2:5] offset:49360
	v_mul_u32_u24_e32 v4, 0x110, v160
	ds_write_b128 v82, v[58:61] offset:49232
	v_add3_u32 v1, v1, v4, v154
	ds_read_b128 v[4:7], v1 offset:49152
	v_or3_b32 v2, v159, s55, v160
	v_mov_b32_e32 v3, v0
	v_lshlrev_b64 v[2:3], 12, v[2:3]
	v_lshlrev_b32_e32 v8, 7, v206
	v_lshl_add_u64 v[2:3], s[18:19], 0, v[2:3]
	v_ashrrev_i32_e32 v9, 31, v8
	v_lshl_add_u64 v[2:3], v[8:9], 1, v[2:3]
	ds_read_b128 v[8:11], v1 offset:50240
	s_waitcnt lgkmcnt(1)
	v_cvt_f32_f16_e32 v12, v4
	v_cvt_f32_f16_sdwa v13, v4 dst_sel:DWORD dst_unused:UNUSED_PAD src0_sel:WORD_1
	s_waitcnt vmcnt(7)
	v_lshlrev_b32_e32 v14, 16, v146
	v_and_b32_e32 v15, 0xffff0000, v146
	v_lshl_add_u64 v[2:3], v[2:3], 0, v[154:155]
	v_mul_f32_e32 v12, v14, v12
	v_mul_f32_e32 v13, v15, v13
	v_cvt_f32_f16_e32 v14, v5
	v_cvt_f32_f16_sdwa v15, v5 dst_sel:DWORD dst_unused:UNUSED_PAD src0_sel:WORD_1
	v_cvt_pk_bf16_f32 v4, v12, v13
	v_lshlrev_b32_e32 v12, 16, v147
	v_and_b32_e32 v13, 0xffff0000, v147
	v_mul_f32_e32 v12, v12, v14
	v_mul_f32_e32 v13, v13, v15
	v_cvt_f32_f16_e32 v14, v6
	v_cvt_f32_f16_sdwa v15, v6 dst_sel:DWORD dst_unused:UNUSED_PAD src0_sel:WORD_1
	v_cvt_pk_bf16_f32 v5, v12, v13
	v_lshlrev_b32_e32 v12, 16, v148
	v_and_b32_e32 v13, 0xffff0000, v148
	v_mul_f32_e32 v12, v12, v14
	v_mul_f32_e32 v13, v13, v15
	v_cvt_f32_f16_e32 v14, v7
	v_cvt_f32_f16_sdwa v15, v7 dst_sel:DWORD dst_unused:UNUSED_PAD src0_sel:WORD_1
	v_cvt_pk_bf16_f32 v6, v12, v13
	v_lshlrev_b32_e32 v12, 16, v149
	v_and_b32_e32 v13, 0xffff0000, v149
	v_mul_f32_e32 v12, v12, v14
	v_mul_f32_e32 v13, v13, v15
	v_add_co_u32_e32 v16, vcc, s16, v2
	v_cvt_pk_bf16_f32 v7, v12, v13
	global_store_dwordx4 v[2:3], v[4:7], off
	s_waitcnt lgkmcnt(0)
	v_cvt_f32_f16_e32 v12, v8
	v_cvt_f32_f16_sdwa v13, v8 dst_sel:DWORD dst_unused:UNUSED_PAD src0_sel:WORD_1
	v_cvt_f32_f16_e32 v6, v9
	v_cvt_f32_f16_sdwa v7, v9 dst_sel:DWORD dst_unused:UNUSED_PAD src0_sel:WORD_1
	s_waitcnt vmcnt(7)
	v_lshlrev_b32_e32 v8, 16, v151
	v_and_b32_e32 v9, 0xffff0000, v151
	v_lshlrev_b32_e32 v4, 16, v150
	v_mul_f32_e32 v6, v8, v6
	v_mul_f32_e32 v7, v9, v7
	v_cvt_f32_f16_e32 v8, v10
	v_cvt_f32_f16_sdwa v9, v10 dst_sel:DWORD dst_unused:UNUSED_PAD src0_sel:WORD_1
	v_and_b32_e32 v5, 0xffff0000, v150
	v_mul_f32_e32 v4, v4, v12
	v_mul_f32_e32 v5, v5, v13
	v_lshlrev_b32_e32 v10, 16, v153
	v_cvt_pk_bf16_f32 v4, v4, v5
	v_cvt_pk_bf16_f32 v5, v6, v7
	v_lshlrev_b32_e32 v6, 16, v152
	v_and_b32_e32 v7, 0xffff0000, v152
	v_mul_f32_e32 v6, v6, v8
	v_mul_f32_e32 v7, v7, v9
	v_cvt_f32_f16_e32 v8, v11
	v_cvt_f32_f16_sdwa v9, v11 dst_sel:DWORD dst_unused:UNUSED_PAD src0_sel:WORD_1
	v_and_b32_e32 v11, 0xffff0000, v153
	v_cvt_pk_bf16_f32 v6, v6, v7
	v_addc_co_u32_e32 v17, vcc, 0, v3, vcc
	v_mul_f32_e32 v8, v10, v8
	v_mul_f32_e32 v9, v11, v9
	ds_read_b128 v[12:15], v1 offset:52416
	v_cvt_pk_bf16_f32 v7, v8, v9
	ds_read_b128 v[8:11], v1 offset:51328
	global_store_dwordx4 v[16:17], v[4:7], off
	s_waitcnt lgkmcnt(0)
	v_cvt_f32_f16_e32 v18, v8
	v_cvt_f32_f16_e32 v6, v9
	v_cvt_f32_f16_sdwa v7, v9 dst_sel:DWORD dst_unused:UNUSED_PAD src0_sel:WORD_1
	v_cvt_f32_f16_sdwa v19, v8 dst_sel:DWORD dst_unused:UNUSED_PAD src0_sel:WORD_1
	s_waitcnt vmcnt(7)
	v_lshlrev_b32_e32 v8, 16, v55
	v_and_b32_e32 v9, 0xffff0000, v55
	v_mul_f32_e32 v6, v8, v6
	v_mul_f32_e32 v7, v9, v7
	v_cvt_f32_f16_e32 v8, v10
	v_cvt_f32_f16_sdwa v9, v10 dst_sel:DWORD dst_unused:UNUSED_PAD src0_sel:WORD_1
	v_lshlrev_b32_e32 v4, 16, v54
	v_and_b32_e32 v5, 0xffff0000, v54
	v_mul_f32_e32 v4, v4, v18
	v_mul_f32_e32 v5, v5, v19
	v_lshlrev_b32_e32 v10, 16, v57
	v_cvt_pk_bf16_f32 v4, v4, v5
	v_cvt_pk_bf16_f32 v5, v6, v7
	v_lshlrev_b32_e32 v6, 16, v56
	v_and_b32_e32 v7, 0xffff0000, v56
	v_mul_f32_e32 v6, v6, v8
	v_mul_f32_e32 v7, v7, v9
	v_cvt_f32_f16_e32 v8, v11
	v_cvt_f32_f16_sdwa v9, v11 dst_sel:DWORD dst_unused:UNUSED_PAD src0_sel:WORD_1
	v_and_b32_e32 v11, 0xffff0000, v57
	v_cvt_pk_bf16_f32 v6, v6, v7
	v_mul_f32_e32 v8, v10, v8
	v_mul_f32_e32 v9, v11, v9
	s_nop 0
	v_cvt_pk_bf16_f32 v7, v8, v9
	v_add_co_u32_e32 v8, vcc, s41, v2
	v_cvt_f32_f16_e32 v10, v12
	s_nop 0
	v_addc_co_u32_e32 v9, vcc, 0, v3, vcc
	global_store_dwordx4 v[8:9], v[4:7], off
	v_cvt_f32_f16_sdwa v11, v12 dst_sel:DWORD dst_unused:UNUSED_PAD src0_sel:WORD_1
	s_waitcnt vmcnt(7)
	v_lshlrev_b32_e32 v8, 16, v51
	v_cvt_f32_f16_e32 v6, v13
	v_cvt_f32_f16_sdwa v7, v13 dst_sel:DWORD dst_unused:UNUSED_PAD src0_sel:WORD_1
	v_and_b32_e32 v9, 0xffff0000, v51
	v_lshlrev_b32_e32 v4, 16, v50
	v_and_b32_e32 v5, 0xffff0000, v50
	v_mul_f32_e32 v6, v8, v6
	v_mul_f32_e32 v7, v9, v7
	v_cvt_f32_f16_e32 v8, v14
	v_cvt_f32_f16_sdwa v9, v14 dst_sel:DWORD dst_unused:UNUSED_PAD src0_sel:WORD_1
	v_mul_f32_e32 v4, v4, v10
	v_mul_f32_e32 v5, v5, v11
	v_lshlrev_b32_e32 v10, 16, v53
	v_cvt_pk_bf16_f32 v4, v4, v5
	v_cvt_pk_bf16_f32 v5, v6, v7
	v_lshlrev_b32_e32 v6, 16, v52
	v_and_b32_e32 v7, 0xffff0000, v52
	v_mul_f32_e32 v6, v6, v8
	v_mul_f32_e32 v7, v7, v9
	v_cvt_f32_f16_e32 v8, v15
	v_cvt_f32_f16_sdwa v9, v15 dst_sel:DWORD dst_unused:UNUSED_PAD src0_sel:WORD_1
	v_and_b32_e32 v11, 0xffff0000, v53
	v_cvt_pk_bf16_f32 v6, v6, v7
	v_add_co_u32_e32 v16, vcc, s50, v2
	v_mul_f32_e32 v8, v10, v8
	v_mul_f32_e32 v9, v11, v9
	s_nop 0
	v_addc_co_u32_e32 v17, vcc, 0, v3, vcc
	v_cvt_pk_bf16_f32 v7, v8, v9
	ds_read_b128 v[8:11], v1 offset:53504
	ds_read_b128 v[12:15], v1 offset:54592
	global_store_dwordx4 v[16:17], v[4:7], off
	s_waitcnt lgkmcnt(1)
	v_cvt_f32_f16_e32 v18, v8
	v_cvt_f32_f16_e32 v6, v9
	v_cvt_f32_f16_sdwa v7, v9 dst_sel:DWORD dst_unused:UNUSED_PAD src0_sel:WORD_1
	v_cvt_f32_f16_sdwa v19, v8 dst_sel:DWORD dst_unused:UNUSED_PAD src0_sel:WORD_1
	s_waitcnt vmcnt(7)
	v_lshlrev_b32_e32 v8, 16, v47
	v_and_b32_e32 v9, 0xffff0000, v47
	v_mul_f32_e32 v6, v8, v6
	v_mul_f32_e32 v7, v9, v7
	v_cvt_f32_f16_e32 v8, v10
	v_cvt_f32_f16_sdwa v9, v10 dst_sel:DWORD dst_unused:UNUSED_PAD src0_sel:WORD_1
	v_lshlrev_b32_e32 v4, 16, v46
	v_and_b32_e32 v5, 0xffff0000, v46
	v_mul_f32_e32 v4, v4, v18
	v_mul_f32_e32 v5, v5, v19
	v_lshlrev_b32_e32 v10, 16, v49
	v_cvt_pk_bf16_f32 v4, v4, v5
	v_cvt_pk_bf16_f32 v5, v6, v7
	v_lshlrev_b32_e32 v6, 16, v48
	v_and_b32_e32 v7, 0xffff0000, v48
	v_mul_f32_e32 v6, v6, v8
	v_mul_f32_e32 v7, v7, v9
	v_cvt_f32_f16_e32 v8, v11
	v_cvt_f32_f16_sdwa v9, v11 dst_sel:DWORD dst_unused:UNUSED_PAD src0_sel:WORD_1
	v_and_b32_e32 v11, 0xffff0000, v49
	v_cvt_pk_bf16_f32 v6, v6, v7
	v_mul_f32_e32 v8, v10, v8
	v_mul_f32_e32 v9, v11, v9
	s_nop 0
	v_cvt_pk_bf16_f32 v7, v8, v9
	v_add_co_u32_e32 v8, vcc, s51, v2
	s_waitcnt lgkmcnt(0)
	v_cvt_f32_f16_e32 v10, v12
	v_addc_co_u32_e32 v9, vcc, 0, v3, vcc
	global_store_dwordx4 v[8:9], v[4:7], off
	v_cvt_f32_f16_sdwa v11, v12 dst_sel:DWORD dst_unused:UNUSED_PAD src0_sel:WORD_1
	s_waitcnt vmcnt(7)
	v_lshlrev_b32_e32 v8, 16, v43
	v_cvt_f32_f16_e32 v6, v13
	v_cvt_f32_f16_sdwa v7, v13 dst_sel:DWORD dst_unused:UNUSED_PAD src0_sel:WORD_1
	v_and_b32_e32 v9, 0xffff0000, v43
	v_lshlrev_b32_e32 v4, 16, v42
	v_and_b32_e32 v5, 0xffff0000, v42
	v_mul_f32_e32 v6, v8, v6
	v_mul_f32_e32 v7, v9, v7
	v_cvt_f32_f16_e32 v8, v14
	v_cvt_f32_f16_sdwa v9, v14 dst_sel:DWORD dst_unused:UNUSED_PAD src0_sel:WORD_1
	v_mul_f32_e32 v4, v4, v10
	v_mul_f32_e32 v5, v5, v11
	v_lshlrev_b32_e32 v10, 16, v45
	v_cvt_pk_bf16_f32 v4, v4, v5
	v_cvt_pk_bf16_f32 v5, v6, v7
	v_lshlrev_b32_e32 v6, 16, v44
	v_and_b32_e32 v7, 0xffff0000, v44
	v_mul_f32_e32 v6, v6, v8
	v_mul_f32_e32 v7, v7, v9
	v_cvt_f32_f16_e32 v8, v15
	v_cvt_f32_f16_sdwa v9, v15 dst_sel:DWORD dst_unused:UNUSED_PAD src0_sel:WORD_1
	v_and_b32_e32 v11, 0xffff0000, v45
	v_cvt_pk_bf16_f32 v6, v6, v7
	v_add_co_u32_e32 v16, vcc, s52, v2
	v_mul_f32_e32 v8, v10, v8
	v_mul_f32_e32 v9, v11, v9
	s_nop 0
	v_addc_co_u32_e32 v17, vcc, 0, v3, vcc
	v_cvt_pk_bf16_f32 v7, v8, v9
	ds_read_b128 v[8:11], v1 offset:55680
	ds_read_b128 v[12:15], v1 offset:56768
	global_store_dwordx4 v[16:17], v[4:7], off
	s_waitcnt lgkmcnt(1)
	v_cvt_f32_f16_e32 v18, v8
	v_cvt_f32_f16_e32 v6, v9
	v_cvt_f32_f16_sdwa v7, v9 dst_sel:DWORD dst_unused:UNUSED_PAD src0_sel:WORD_1
	v_cvt_f32_f16_sdwa v19, v8 dst_sel:DWORD dst_unused:UNUSED_PAD src0_sel:WORD_1
	s_waitcnt vmcnt(7)
	v_lshlrev_b32_e32 v8, 16, v39
	v_and_b32_e32 v9, 0xffff0000, v39
	v_mul_f32_e32 v6, v8, v6
	v_mul_f32_e32 v7, v9, v7
	v_cvt_f32_f16_e32 v8, v10
	v_cvt_f32_f16_sdwa v9, v10 dst_sel:DWORD dst_unused:UNUSED_PAD src0_sel:WORD_1
	v_lshlrev_b32_e32 v4, 16, v38
	v_and_b32_e32 v5, 0xffff0000, v38
	v_mul_f32_e32 v4, v4, v18
	v_mul_f32_e32 v5, v5, v19
	v_lshlrev_b32_e32 v10, 16, v41
	v_cvt_pk_bf16_f32 v4, v4, v5
	v_cvt_pk_bf16_f32 v5, v6, v7
	v_lshlrev_b32_e32 v6, 16, v40
	v_and_b32_e32 v7, 0xffff0000, v40
	v_mul_f32_e32 v6, v6, v8
	v_mul_f32_e32 v7, v7, v9
	v_cvt_f32_f16_e32 v8, v11
	v_cvt_f32_f16_sdwa v9, v11 dst_sel:DWORD dst_unused:UNUSED_PAD src0_sel:WORD_1
	v_and_b32_e32 v11, 0xffff0000, v41
	v_cvt_pk_bf16_f32 v6, v6, v7
	v_mul_f32_e32 v8, v10, v8
	v_mul_f32_e32 v9, v11, v9
	s_nop 0
	v_cvt_pk_bf16_f32 v7, v8, v9
	v_add_co_u32_e32 v8, vcc, s53, v2
	s_waitcnt lgkmcnt(0)
	v_cvt_f32_f16_e32 v10, v12
	v_addc_co_u32_e32 v9, vcc, 0, v3, vcc
	global_store_dwordx4 v[8:9], v[4:7], off
	v_cvt_f32_f16_sdwa v11, v12 dst_sel:DWORD dst_unused:UNUSED_PAD src0_sel:WORD_1
	s_waitcnt vmcnt(7)
	v_lshlrev_b32_e32 v8, 16, v35
	v_cvt_f32_f16_e32 v6, v13
	v_cvt_f32_f16_sdwa v7, v13 dst_sel:DWORD dst_unused:UNUSED_PAD src0_sel:WORD_1
	v_and_b32_e32 v9, 0xffff0000, v35
	v_lshlrev_b32_e32 v4, 16, v34
	v_and_b32_e32 v5, 0xffff0000, v34
	v_mul_f32_e32 v6, v8, v6
	v_mul_f32_e32 v7, v9, v7
	v_cvt_f32_f16_e32 v8, v14
	v_cvt_f32_f16_sdwa v9, v14 dst_sel:DWORD dst_unused:UNUSED_PAD src0_sel:WORD_1
	v_mul_f32_e32 v4, v4, v10
	v_mul_f32_e32 v5, v5, v11
	v_lshlrev_b32_e32 v10, 16, v37
	v_cvt_pk_bf16_f32 v4, v4, v5
	v_cvt_pk_bf16_f32 v5, v6, v7
	v_lshlrev_b32_e32 v6, 16, v36
	v_and_b32_e32 v7, 0xffff0000, v36
	v_mul_f32_e32 v6, v6, v8
	v_mul_f32_e32 v7, v7, v9
	v_cvt_f32_f16_e32 v8, v15
	v_cvt_f32_f16_sdwa v9, v15 dst_sel:DWORD dst_unused:UNUSED_PAD src0_sel:WORD_1
	v_and_b32_e32 v11, 0xffff0000, v37
	v_add_co_u32_e32 v2, vcc, 0x1c000, v2
	v_mul_f32_e32 v8, v10, v8
	v_mul_f32_e32 v9, v11, v9
	v_cvt_pk_bf16_f32 v6, v6, v7
	v_cvt_pk_bf16_f32 v7, v8, v9
	v_addc_co_u32_e32 v3, vcc, 0, v3, vcc
	global_store_dwordx4 v[2:3], v[4:7], off
